# LN0 gate-weight staging: the four trips' strided w_in loads issued together (prologue de-serialisation); bit-identical
# baseline (speedup 1.0000x reference)
; template <bool GATES, bool WRITE_B, bool WRITE_F, bool SRC_BF16> ...
;     ...
;     if (GATES) {
;         for (int k = tid; k < D; k += NTHREADS) {
;             const f32x4 a = *(const f32x4*)(win_l + (size_t)k * NSRC + 4096), c = *(const f32x4*)(win_l + (size_t)k * NSRC + 4100);
;             wg[0 * D + k] = a[0]; wg[1 * D + k] = a[1]; wg[2 * D + k] = a[2]; wg[3 * D + k] = a[3];
;             wg[4 * D + k] = c[0]; wg[5 * D + k] = c[1]; wg[6 * D + k] = c[2]; wg[7 * D + k] = c[3];
;         }
;         __syncthreads();
.LBB0_59:
	v_lshl_add_u64 v[30:31], v[2:3], 0, s[26:27]
	v_lshl_add_u64 v[32:33], v[30:31], 0, s[26:27]
	v_lshl_add_u64 v[34:35], v[32:33], 0, s[26:27]
	global_load_dwordx4 v[6:9], v[2:3], off
	global_load_dwordx4 v[10:13], v[2:3], off offset:16
	global_load_dwordx4 v[14:17], v[30:31], off
	global_load_dwordx4 v[18:21], v[30:31], off offset:16
	global_load_dwordx4 v[22:25], v[32:33], off
	global_load_dwordx4 v[26:29], v[32:33], off offset:16
	global_load_dwordx4 v[36:39], v[34:35], off
	global_load_dwordx4 v[40:43], v[34:35], off offset:16
	s_waitcnt vmcnt(7)
	ds_write2st64_b32 v5, v6, v7 offset0:0 offset1:32
	ds_write2st64_b32 v5, v8, v9 offset0:64 offset1:96
	s_waitcnt vmcnt(6)
	ds_write2st64_b32 v5, v10, v11 offset0:128 offset1:160
	ds_write2st64_b32 v5, v12, v13 offset0:192 offset1:224
	s_waitcnt vmcnt(5)
	ds_write2st64_b32 v5, v14, v15 offset0:8 offset1:40
	ds_write2st64_b32 v5, v16, v17 offset0:72 offset1:104
	s_waitcnt vmcnt(4)
	ds_write2st64_b32 v5, v18, v19 offset0:136 offset1:168
	ds_write2st64_b32 v5, v20, v21 offset0:200 offset1:232
	s_waitcnt vmcnt(3)
	ds_write2st64_b32 v5, v22, v23 offset0:16 offset1:48
	ds_write2st64_b32 v5, v24, v25 offset0:80 offset1:112
	s_waitcnt vmcnt(2)
	ds_write2st64_b32 v5, v26, v27 offset0:144 offset1:176
	ds_write2st64_b32 v5, v28, v29 offset0:208 offset1:240
	s_waitcnt vmcnt(1)
	ds_write2st64_b32 v5, v36, v37 offset0:24 offset1:56
	ds_write2st64_b32 v5, v38, v39 offset0:88 offset1:120
	s_waitcnt vmcnt(0)
	ds_write2st64_b32 v5, v40, v41 offset0:152 offset1:184
	ds_write2st64_b32 v5, v42, v43 offset0:216 offset1:248
